# GDN pre conv, k waves: the two per-token LDS reads (gate values) issued at the start of the token's arithmetic instead of right before use
# speedup vs baseline: 1.0076x; 1.0076x over previous
; DI unsigned pk2(float lo, float hi) { f32x2 v = {lo, hi}; bf16x2_t b = __builtin_convertvector(v, bf16x2_t); return __builtin_bit_cast(unsigned, b); }
; DI bf16_t f2bf(float f) { return (bf16_t)(pk2(f, 0.f) & 0xffffu); }
; DI float siluf(float x) { return x * __builtin_amdgcn_rcpf(1.f + __expf(-x)); }
; template <class F> DI void gdn_conv(const Prm& p, int kind, int b, int c, int col, int t0, int n, F f) {
;     ...
;     for (int t = t0; t < t0 + n; ++t) { const f32x2 x3 = gdn_raw(p, kind, b, c, t, col);
;         const float y0 = w[0].x * x0.x + w[1].x * x1.x + w[2].x * x2.x + w[3].x * x3.x, y1 = w[0].y * x0.y + w[1].y * x1.y + w[2].y * x2.y + w[3].y * x3.y;
;         f(t, siluf(y0), siluf(y1)); x0 = x1; x1 = x2; x2 = x3; }
; DI void gdn_pre_unit(const Prm& p, unsigned char* lds0, int u, int tid, int wid, int lane) {
;     ...
;         gdn_conv(p, kind, b, c, part * 512 + h * 128 + 2 * lane, 32 * th, 32, [&](int t, float y0, float y1) {
;             if (part == 2) { vtL[(2 * lane) * GT_STR + t] = f2bf(y0); vtL[(2 * lane + 1) * GT_STR + t] = f2bf(y1); }
;             else { const float ss = wave_sum(y0 * y0 + y1 * y1); float rn = rsqrtf(ss + 1e-6f);
;                 if (part == 0) { rn *= 0.08838834764831845f; *(unsigned*)(qL + t * GK_STR + 2 * lane) = pk2(y0 * rn, y1 * rn); }
;                 else { const float k0 = y0 * rn, k1 = y1 * rn; *(unsigned*)(kL + t * GK_STR + 2 * lane) = pk2(k0, k1); const float eg = gL[128 + t], ed = __expf(gl - gL[t]);
;                     kegL[(2 * lane) * GT_STR + t] = f2bf(k0 * eg); kegL[(2 * lane + 1) * GT_STR + t] = f2bf(k1 * eg); kdL[(2 * lane) * GT_STR + t] = f2bf(k0 * ed); kdL[(2 * lane + 1) * GT_STR + t] = f2bf(k1 * ed); } } });
.LBB0_1223:
	s_add_i32 s98, s25, s88
	s_add_i32 s99, s98, 0x1c400
	s_add_i32 s98, s98, 0x1c600
	v_mov_b32_e32 v70, s98
	v_mov_b32_e32 v71, s99
	ds_read_b32 v72, v70
	ds_read_b32 v73, v71
	v_pk_mul_f32 v[30:31], v[2:3], v[20:21]
	s_mov_b64 s[8:9], -1
	v_pk_fma_f32 v[18:19], v[0:1], v[18:19], v[30:31]
	s_and_b64 vcc, exec, s[72:73]
	v_pk_fma_f32 v[18:19], v[4:5], v[22:23], v[18:19]
	s_nop 0
	v_pk_fma_f32 v[18:19], v[6:7], v[24:25], v[18:19]
	s_nop 0
	v_mul_f32_e32 v26, 0xbfb8aa3b, v18
	v_mul_f32_e32 v30, 0xbfb8aa3b, v19
	v_exp_f32_e32 v26, v26
	v_exp_f32_e32 v30, v30
	v_add_f32_e32 v26, 1.0, v26
	v_add_f32_e32 v31, 1.0, v30
	v_rcp_f32_e32 v30, v26
	v_rcp_f32_e32 v31, v31
	s_nop 0
	v_pk_mul_f32 v[18:19], v[18:19], v[30:31]
	s_cbranch_vccz .LBB0_1229
	v_pk_mul_f32 v[30:31], v[18:19], v[18:19]
	s_nop 0
	v_add_f32_e32 v26, v30, v31
	s_nop 1
	v_add_f32_dpp v26, v26, v26 quad_perm:[1,0,3,2] row_mask:0xf bank_mask:0xf bound_ctrl:1
	s_nop 1
	v_add_f32_dpp v26, v26, v26 quad_perm:[2,3,0,1] row_mask:0xf bank_mask:0xf bound_ctrl:1
	s_nop 1
	v_add_f32_dpp v26, v26, v26 row_half_mirror row_mask:0xf bank_mask:0xf bound_ctrl:1
	s_nop 1
	v_add_f32_dpp v26, v26, v26 row_mirror row_mask:0xf bank_mask:0xf bound_ctrl:1
	s_nop 0
	v_readlane_b32 s10, v26, 16
	v_readlane_b32 s11, v26, 48
	v_readlane_b32 s8, v26, 0
	v_readlane_b32 s9, v26, 32
	v_mov_b32_e32 v30, s10
	v_mov_b32_e32 v31, s11
	v_pk_add_f32 v[30:31], s[8:9], v[30:31]
	s_mov_b64 s[8:9], -1
	v_add_f32_e32 v26, v30, v31
	v_add_f32_e32 v26, 0x358637bd, v26
	v_mul_f32_e32 v30, 0x4b800000, v26
	v_cmp_gt_f32_e32 vcc, s78, v26
	s_nop 1
	v_cndmask_b32_e32 v26, v26, v30, vcc
	v_rsq_f32_e32 v26, v26
	s_nop 0
	v_mul_f32_e32 v30, 0x45800000, v26
	v_cndmask_b32_e32 v26, v26, v30, vcc
	s_and_b64 vcc, exec, s[54:55]
	s_cbranch_vccz .LBB0_1226
	s_waitcnt lgkmcnt(2)
	v_pk_mul_f32 v[30:31], v[18:19], v[26:27] op_sel_hi:[1,0]
	v_add_u32_e32 v45, s88, v29
	v_cvt_pk_bf16_f32 v44, v30, v31
	ds_write_b32 v45, v44 offset:17408
	s_waitcnt lgkmcnt(1)
	v_sub_f32_e32 v35, v27, v73
	v_mul_f32_e32 v35, 0x3fb8aa3b, v35
	v_exp_f32_e32 v35, v35
	v_mul_f32_e32 v44, v30, v72
	v_mul_f32_e32 v32, v31, v72
	v_add_u32_e32 v45, s88, v28
	v_cvt_pk_bf16_f32 v32, v32, s0
	v_mul_f32_e32 v30, v30, v35
	ds_write_b16 v45, v32 offset:34960
	v_cvt_pk_bf16_f32 v30, v30, s0
	v_add_u32_e32 v32, 0x11800, v45
	ds_write_b16 v32, v30
	v_mul_f32_e32 v30, v31, v35
	v_cvt_pk_bf16_f32 v44, v44, s0
	v_cvt_pk_bf16_f32 v30, v30, s0
	v_add_u32_e32 v31, 0x11890, v45
	ds_write_b16 v45, v44 offset:34816
	ds_write_b16 v31, v30
	s_mov_b64 s[8:9], 0

; DI unsigned pk2(float lo, float hi) { f32x2 v = {lo, hi}; bf16x2_t b = __builtin_convertvector(v, bf16x2_t); return __builtin_bit_cast(unsigned, b); }
; DI bf16_t f2bf(float f) { return (bf16_t)(pk2(f, 0.f) & 0xffffu); }
; DI float siluf(float x) { return x * __builtin_amdgcn_rcpf(1.f + __expf(-x)); }
; template <class F> DI void gdn_conv(const Prm& p, int kind, int b, int c, int col, int t0, int n, F f) {
;     ...
;     for (int t = t0; t < t0 + n; ++t) { const f32x2 x3 = gdn_raw(p, kind, b, c, t, col);
;         const float y0 = w[0].x * x0.x + w[1].x * x1.x + w[2].x * x2.x + w[3].x * x3.x, y1 = w[0].y * x0.y + w[1].y * x1.y + w[2].y * x2.y + w[3].y * x3.y;
;         f(t, siluf(y0), siluf(y1)); x0 = x1; x1 = x2; x2 = x3; }
; DI void gdn_pre_unit(const Prm& p, unsigned char* lds0, int u, int tid, int wid, int lane) {
;     ...
;         gdn_conv(p, kind, b, c, part * 512 + h * 128 + 2 * lane, 32 * th, 32, [&](int t, float y0, float y1) {
;             if (part == 2) { vtL[(2 * lane) * GT_STR + t] = f2bf(y0); vtL[(2 * lane + 1) * GT_STR + t] = f2bf(y1); }
;             else { const float ss = wave_sum(y0 * y0 + y1 * y1); float rn = rsqrtf(ss + 1e-6f);
;                 if (part == 0) { rn *= 0.08838834764831845f; *(unsigned*)(qL + t * GK_STR + 2 * lane) = pk2(y0 * rn, y1 * rn); }
;                 else { const float k0 = y0 * rn, k1 = y1 * rn; *(unsigned*)(kL + t * GK_STR + 2 * lane) = pk2(k0, k1); const float eg = gL[128 + t], ed = __expf(gl - gL[t]);
;                     kegL[(2 * lane) * GT_STR + t] = f2bf(k0 * eg); kegL[(2 * lane + 1) * GT_STR + t] = f2bf(k1 * eg); kdL[(2 * lane) * GT_STR + t] = f2bf(k0 * ed); kdL[(2 * lane + 1) * GT_STR + t] = f2bf(k1 * ed); } } });
.LBB0_1241:
	s_add_i32 s98, s25, s88
	s_add_i32 s99, s98, 0x1c404
	s_add_i32 s98, s98, 0x1c604
	v_mov_b32_e32 v70, s98
	v_mov_b32_e32 v71, s99
	ds_read_b32 v72, v70
	ds_read_b32 v73, v71
	v_pk_mul_f32 v[44:45], v[2:3], v[22:23]
	s_mov_b64 s[16:17], -1
	v_pk_fma_f32 v[20:21], v[0:1], v[20:21], v[44:45]
	s_andn2_b64 vcc, exec, s[72:73]
	v_pk_fma_f32 v[20:21], v[4:5], v[24:25], v[20:21]
	v_pk_fma_f32 v[20:21], v[6:7], v[18:19], v[20:21]
	s_nop 0
	v_mul_f32_e32 v26, 0xbfb8aa3b, v20
	v_exp_f32_e32 v26, v26
	s_nop 0
	v_add_f32_e32 v26, 1.0, v26
	v_rcp_f32_e32 v44, v26
	v_mul_f32_e32 v26, 0xbfb8aa3b, v21
	v_exp_f32_e32 v26, v26
	s_nop 0
	v_add_f32_e32 v26, 1.0, v26
	v_rcp_f32_e32 v45, v26
	v_cndmask_b32_e64 v26, 0, 1, s[72:73]
	v_cmp_ne_u32_e64 s[12:13], 1, v26
	v_cndmask_b32_e64 v26, 0, 1, s[54:55]
	v_pk_mul_f32 v[20:21], v[20:21], v[44:45]
	v_cmp_ne_u32_e64 s[8:9], 1, v26
	s_cbranch_vccnz .LBB0_1247
	v_pk_mul_f32 v[44:45], v[20:21], v[20:21]
	s_nop 0
	v_add_f32_e32 v26, v44, v45
	s_nop 1
	v_add_f32_dpp v26, v26, v26 quad_perm:[1,0,3,2] row_mask:0xf bank_mask:0xf bound_ctrl:1
	s_nop 1
	v_add_f32_dpp v26, v26, v26 quad_perm:[2,3,0,1] row_mask:0xf bank_mask:0xf bound_ctrl:1
	s_nop 1
	v_add_f32_dpp v26, v26, v26 row_half_mirror row_mask:0xf bank_mask:0xf bound_ctrl:1
	s_nop 1
	v_add_f32_dpp v26, v26, v26 row_mirror row_mask:0xf bank_mask:0xf bound_ctrl:1
	s_nop 0
	v_readlane_b32 s36, v26, 16
	v_readlane_b32 s37, v26, 48
	v_readlane_b32 s16, v26, 0
	v_readlane_b32 s17, v26, 32
	v_mov_b32_e32 v44, s36
	v_mov_b32_e32 v45, s37
	v_pk_add_f32 v[44:45], s[16:17], v[44:45]
	s_mov_b64 s[16:17], -1
	v_add_f32_e32 v26, v44, v45
	v_add_f32_e32 v26, 0x358637bd, v26
	v_mul_f32_e32 v31, 0x4b800000, v26
	v_cmp_gt_f32_e32 vcc, s78, v26
	s_nop 1
	v_cndmask_b32_e32 v26, v26, v31, vcc
	v_rsq_f32_e32 v26, v26
	s_nop 0
	v_mul_f32_e32 v31, 0x45800000, v26
	v_cndmask_b32_e32 v26, v26, v31, vcc
	s_and_b64 vcc, exec, s[8:9]
	s_cbranch_vccnz .LBB0_1244
	s_waitcnt lgkmcnt(2)
	v_pk_mul_f32 v[44:45], v[20:21], v[26:27] op_sel_hi:[1,0]
	v_add_u32_e32 v46, s88, v29
	v_cvt_pk_bf16_f32 v35, v44, v45
	ds_write_b32 v46, v35 offset:17680
	s_waitcnt lgkmcnt(1)
	v_sub_f32_e32 v32, v27, v73
	v_mul_f32_e32 v32, 0x3fb8aa3b, v32
	v_exp_f32_e32 v32, v32
	v_mul_f32_e32 v35, v44, v72
	v_mul_f32_e32 v31, v45, v72
	v_cvt_pk_bf16_f32 v31, v31, s0
	v_cvt_pk_bf16_f32 v35, v35, s0
	ds_write_b16 v30, v31 offset:34962
	v_mul_f32_e32 v31, v44, v32
	ds_write_b16 v30, v35 offset:34818
	v_cvt_pk_bf16_f32 v31, v31, s0
	v_add_u32_e32 v35, 0x11802, v30
	ds_write_b16 v35, v31
	v_mul_f32_e32 v31, v45, v32
	v_cvt_pk_bf16_f32 v31, v31, s0
	v_add_u32_e32 v32, 0x11892, v30
	s_mov_b64 s[16:17], 0
	ds_write_b16 v32, v31

; DI unsigned pk2(float lo, float hi) { f32x2 v = {lo, hi}; bf16x2_t b = __builtin_convertvector(v, bf16x2_t); return __builtin_bit_cast(unsigned, b); }
; DI bf16_t f2bf(float f) { return (bf16_t)(pk2(f, 0.f) & 0xffffu); }
; DI float siluf(float x) { return x * __builtin_amdgcn_rcpf(1.f + __expf(-x)); }
; template <class F> DI void gdn_conv(const Prm& p, int kind, int b, int c, int col, int t0, int n, F f) {
;     ...
;     for (int t = t0; t < t0 + n; ++t) { const f32x2 x3 = gdn_raw(p, kind, b, c, t, col);
;         const float y0 = w[0].x * x0.x + w[1].x * x1.x + w[2].x * x2.x + w[3].x * x3.x, y1 = w[0].y * x0.y + w[1].y * x1.y + w[2].y * x2.y + w[3].y * x3.y;
;         f(t, siluf(y0), siluf(y1)); x0 = x1; x1 = x2; x2 = x3; }
; DI void gdn_pre_unit(const Prm& p, unsigned char* lds0, int u, int tid, int wid, int lane) {
;     ...
;         gdn_conv(p, kind, b, c, part * 512 + h * 128 + 2 * lane, 32 * th, 32, [&](int t, float y0, float y1) {
;             if (part == 2) { vtL[(2 * lane) * GT_STR + t] = f2bf(y0); vtL[(2 * lane + 1) * GT_STR + t] = f2bf(y1); }
;             else { const float ss = wave_sum(y0 * y0 + y1 * y1); float rn = rsqrtf(ss + 1e-6f);
;                 if (part == 0) { rn *= 0.08838834764831845f; *(unsigned*)(qL + t * GK_STR + 2 * lane) = pk2(y0 * rn, y1 * rn); }
;                 else { const float k0 = y0 * rn, k1 = y1 * rn; *(unsigned*)(kL + t * GK_STR + 2 * lane) = pk2(k0, k1); const float eg = gL[128 + t], ed = __expf(gl - gL[t]);
;                     kegL[(2 * lane) * GT_STR + t] = f2bf(k0 * eg); kegL[(2 * lane + 1) * GT_STR + t] = f2bf(k1 * eg); kdL[(2 * lane) * GT_STR + t] = f2bf(k0 * ed); kdL[(2 * lane + 1) * GT_STR + t] = f2bf(k1 * ed); } } });
.LBB0_1259:
	s_add_i32 s98, s25, s88
	s_add_i32 s99, s98, 0x1c408
	s_add_i32 s98, s98, 0x1c608
	v_mov_b32_e32 v70, s98
	v_mov_b32_e32 v71, s99
	ds_read_b32 v72, v70
	ds_read_b32 v73, v71
	v_pk_mul_f32 v[44:45], v[2:3], v[24:25]
	s_and_b64 vcc, exec, s[12:13]
	v_pk_fma_f32 v[22:23], v[0:1], v[22:23], v[44:45]
	s_mov_b64 s[16:17], -1
	v_pk_fma_f32 v[22:23], v[4:5], v[18:19], v[22:23]
	v_pk_fma_f32 v[22:23], v[6:7], v[20:21], v[22:23]
	s_nop 0
	v_mul_f32_e32 v26, 0xbfb8aa3b, v22
	v_mul_f32_e32 v31, 0xbfb8aa3b, v23
	v_exp_f32_e32 v26, v26
	v_exp_f32_e32 v31, v31
	v_add_f32_e32 v26, 1.0, v26
	v_add_f32_e32 v31, 1.0, v31
	v_rcp_f32_e32 v44, v26
	v_rcp_f32_e32 v45, v31
	s_nop 0
	v_pk_mul_f32 v[22:23], v[22:23], v[44:45]
	s_cbranch_vccnz .LBB0_1265
	v_pk_mul_f32 v[44:45], v[22:23], v[22:23]
	s_nop 0
	v_add_f32_e32 v26, v44, v45
	s_nop 1
	v_add_f32_dpp v26, v26, v26 quad_perm:[1,0,3,2] row_mask:0xf bank_mask:0xf bound_ctrl:1
	s_nop 1
	v_add_f32_dpp v26, v26, v26 quad_perm:[2,3,0,1] row_mask:0xf bank_mask:0xf bound_ctrl:1
	s_nop 1
	v_add_f32_dpp v26, v26, v26 row_half_mirror row_mask:0xf bank_mask:0xf bound_ctrl:1
	s_nop 1
	v_add_f32_dpp v26, v26, v26 row_mirror row_mask:0xf bank_mask:0xf bound_ctrl:1
	s_nop 0
	v_readlane_b32 s36, v26, 16
	v_readlane_b32 s37, v26, 48
	v_readlane_b32 s16, v26, 0
	v_readlane_b32 s17, v26, 32
	v_mov_b32_e32 v44, s36
	v_mov_b32_e32 v45, s37
	v_pk_add_f32 v[44:45], s[16:17], v[44:45]
	s_mov_b64 s[16:17], -1
	v_add_f32_e32 v26, v44, v45
	v_add_f32_e32 v26, 0x358637bd, v26
	v_mul_f32_e32 v31, 0x4b800000, v26
	v_cmp_gt_f32_e32 vcc, s78, v26
	s_nop 1
	v_cndmask_b32_e32 v26, v26, v31, vcc
	v_rsq_f32_e32 v26, v26
	s_nop 0
	v_mul_f32_e32 v31, 0x45800000, v26
	v_cndmask_b32_e32 v26, v26, v31, vcc
	s_and_b64 vcc, exec, s[8:9]
	s_cbranch_vccnz .LBB0_1262
	s_waitcnt lgkmcnt(2)
	v_pk_mul_f32 v[44:45], v[22:23], v[26:27] op_sel_hi:[1,0]
	v_add_u32_e32 v46, s88, v29
	v_cvt_pk_bf16_f32 v35, v44, v45
	ds_write_b32 v46, v35 offset:17952
	s_waitcnt lgkmcnt(1)
	v_sub_f32_e32 v32, v27, v73
	v_mul_f32_e32 v32, 0x3fb8aa3b, v32
	v_exp_f32_e32 v32, v32
	v_mul_f32_e32 v35, v44, v72
	v_mul_f32_e32 v31, v45, v72
	v_cvt_pk_bf16_f32 v31, v31, s0
	v_cvt_pk_bf16_f32 v35, v35, s0
	ds_write_b16 v30, v31 offset:34964
	v_mul_f32_e32 v31, v44, v32
	ds_write_b16 v30, v35 offset:34820
	v_cvt_pk_bf16_f32 v31, v31, s0
	v_add_u32_e32 v35, 0x11804, v30
	ds_write_b16 v35, v31
	v_mul_f32_e32 v31, v45, v32
	v_cvt_pk_bf16_f32 v31, v31, s0
	v_add_u32_e32 v32, 0x11894, v30
	s_mov_b64 s[16:17], 0
	ds_write_b16 v32, v31

; DI unsigned pk2(float lo, float hi) { f32x2 v = {lo, hi}; bf16x2_t b = __builtin_convertvector(v, bf16x2_t); return __builtin_bit_cast(unsigned, b); }
; DI bf16_t f2bf(float f) { return (bf16_t)(pk2(f, 0.f) & 0xffffu); }
; DI float siluf(float x) { return x * __builtin_amdgcn_rcpf(1.f + __expf(-x)); }
; template <class F> DI void gdn_conv(const Prm& p, int kind, int b, int c, int col, int t0, int n, F f) {
;     ...
;     for (int t = t0; t < t0 + n; ++t) { const f32x2 x3 = gdn_raw(p, kind, b, c, t, col);
;         const float y0 = w[0].x * x0.x + w[1].x * x1.x + w[2].x * x2.x + w[3].x * x3.x, y1 = w[0].y * x0.y + w[1].y * x1.y + w[2].y * x2.y + w[3].y * x3.y;
;         f(t, siluf(y0), siluf(y1)); x0 = x1; x1 = x2; x2 = x3; }
; DI void gdn_pre_unit(const Prm& p, unsigned char* lds0, int u, int tid, int wid, int lane) {
;     ...
;         gdn_conv(p, kind, b, c, part * 512 + h * 128 + 2 * lane, 32 * th, 32, [&](int t, float y0, float y1) {
;             if (part == 2) { vtL[(2 * lane) * GT_STR + t] = f2bf(y0); vtL[(2 * lane + 1) * GT_STR + t] = f2bf(y1); }
;             else { const float ss = wave_sum(y0 * y0 + y1 * y1); float rn = rsqrtf(ss + 1e-6f);
;                 if (part == 0) { rn *= 0.08838834764831845f; *(unsigned*)(qL + t * GK_STR + 2 * lane) = pk2(y0 * rn, y1 * rn); }
;                 else { const float k0 = y0 * rn, k1 = y1 * rn; *(unsigned*)(kL + t * GK_STR + 2 * lane) = pk2(k0, k1); const float eg = gL[128 + t], ed = __expf(gl - gL[t]);
;                     kegL[(2 * lane) * GT_STR + t] = f2bf(k0 * eg); kegL[(2 * lane + 1) * GT_STR + t] = f2bf(k1 * eg); kdL[(2 * lane) * GT_STR + t] = f2bf(k0 * ed); kdL[(2 * lane + 1) * GT_STR + t] = f2bf(k1 * ed); } } });
.LBB0_1277:
	s_add_i32 s98, s25, s88
	s_add_i32 s99, s98, 0x1c40c
	s_add_i32 s98, s98, 0x1c60c
	v_mov_b32_e32 v70, s98
	v_mov_b32_e32 v71, s99
	ds_read_b32 v72, v70
	ds_read_b32 v73, v71
	v_pk_mul_f32 v[44:45], v[2:3], v[18:19]
	s_and_b64 vcc, exec, s[12:13]
	v_pk_fma_f32 v[24:25], v[0:1], v[24:25], v[44:45]
	s_mov_b64 s[16:17], -1
	v_pk_fma_f32 v[24:25], v[4:5], v[20:21], v[24:25]
	v_pk_fma_f32 v[24:25], v[6:7], v[22:23], v[24:25]
	s_nop 0
	v_mul_f32_e32 v26, 0xbfb8aa3b, v24
	v_mul_f32_e32 v31, 0xbfb8aa3b, v25
	v_exp_f32_e32 v26, v26
	v_exp_f32_e32 v31, v31
	v_add_f32_e32 v26, 1.0, v26
	v_add_f32_e32 v31, 1.0, v31
	v_rcp_f32_e32 v44, v26
	v_rcp_f32_e32 v45, v31
	s_nop 0
	v_pk_mul_f32 v[24:25], v[24:25], v[44:45]
	s_cbranch_vccnz .LBB0_1283
	v_pk_mul_f32 v[44:45], v[24:25], v[24:25]
	s_nop 0
	v_add_f32_e32 v26, v44, v45
	s_nop 1
	v_add_f32_dpp v26, v26, v26 quad_perm:[1,0,3,2] row_mask:0xf bank_mask:0xf bound_ctrl:1
	s_nop 1
	v_add_f32_dpp v26, v26, v26 quad_perm:[2,3,0,1] row_mask:0xf bank_mask:0xf bound_ctrl:1
	s_nop 1
	v_add_f32_dpp v26, v26, v26 row_half_mirror row_mask:0xf bank_mask:0xf bound_ctrl:1
	s_nop 1
	v_add_f32_dpp v26, v26, v26 row_mirror row_mask:0xf bank_mask:0xf bound_ctrl:1
	s_nop 0
	v_readlane_b32 s36, v26, 16
	v_readlane_b32 s37, v26, 48
	v_readlane_b32 s16, v26, 0
	v_readlane_b32 s17, v26, 32
	v_mov_b32_e32 v44, s36
	v_mov_b32_e32 v45, s37
	v_pk_add_f32 v[44:45], s[16:17], v[44:45]
	s_mov_b64 s[16:17], -1
	v_add_f32_e32 v26, v44, v45
	v_add_f32_e32 v26, 0x358637bd, v26
	v_mul_f32_e32 v31, 0x4b800000, v26
	v_cmp_gt_f32_e32 vcc, s78, v26
	s_nop 1
	v_cndmask_b32_e32 v26, v26, v31, vcc
	v_rsq_f32_e32 v26, v26
	s_nop 0
	v_mul_f32_e32 v31, 0x45800000, v26
	v_cndmask_b32_e32 v26, v26, v31, vcc
	s_and_b64 vcc, exec, s[8:9]
	s_cbranch_vccnz .LBB0_1280
	s_waitcnt lgkmcnt(2)
	v_pk_mul_f32 v[44:45], v[24:25], v[26:27] op_sel_hi:[1,0]
	v_add_u32_e32 v46, s88, v29
	v_cvt_pk_bf16_f32 v35, v44, v45
	ds_write_b32 v46, v35 offset:18224
	s_waitcnt lgkmcnt(1)
	v_sub_f32_e32 v32, v27, v73
	v_mul_f32_e32 v32, 0x3fb8aa3b, v32
	v_exp_f32_e32 v32, v32
	v_mul_f32_e32 v35, v44, v72
	v_mul_f32_e32 v31, v45, v72
	v_cvt_pk_bf16_f32 v31, v31, s0
	v_cvt_pk_bf16_f32 v35, v35, s0
	ds_write_b16 v30, v31 offset:34966
	v_mul_f32_e32 v31, v44, v32
	ds_write_b16 v30, v35 offset:34822
	v_cvt_pk_bf16_f32 v31, v31, s0
	v_add_u32_e32 v35, 0x11806, v30
	ds_write_b16 v35, v31
	v_mul_f32_e32 v31, v45, v32
	v_cvt_pk_bf16_f32 v31, v31, s0
	v_add_u32_e32 v32, 0x11896, v30
	s_mov_b64 s[16:17], 0
	ds_write_b16 v32, v31

; DI unsigned pk2(float lo, float hi) { f32x2 v = {lo, hi}; bf16x2_t b = __builtin_convertvector(v, bf16x2_t); return __builtin_bit_cast(unsigned, b); }
; DI bf16_t f2bf(float f) { return (bf16_t)(pk2(f, 0.f) & 0xffffu); }
; DI float siluf(float x) { return x * __builtin_amdgcn_rcpf(1.f + __expf(-x)); }
; template <class F> DI void gdn_conv(const Prm& p, int kind, int b, int c, int col, int t0, int n, F f) {
;     ...
;     for (int t = t0; t < t0 + n; ++t) { const f32x2 x3 = gdn_raw(p, kind, b, c, t, col);
;         const float y0 = w[0].x * x0.x + w[1].x * x1.x + w[2].x * x2.x + w[3].x * x3.x, y1 = w[0].y * x0.y + w[1].y * x1.y + w[2].y * x2.y + w[3].y * x3.y;
;         f(t, siluf(y0), siluf(y1)); x0 = x1; x1 = x2; x2 = x3; }
; DI void gdn_pre_unit(const Prm& p, unsigned char* lds0, int u, int tid, int wid, int lane) {
;     ...
;         gdn_conv(p, kind, b, c, part * 512 + h * 128 + 2 * lane, 32 * th, 32, [&](int t, float y0, float y1) {
;             if (part == 2) { vtL[(2 * lane) * GT_STR + t] = f2bf(y0); vtL[(2 * lane + 1) * GT_STR + t] = f2bf(y1); }
;             else { const float ss = wave_sum(y0 * y0 + y1 * y1); float rn = rsqrtf(ss + 1e-6f);
;                 if (part == 0) { rn *= 0.08838834764831845f; *(unsigned*)(qL + t * GK_STR + 2 * lane) = pk2(y0 * rn, y1 * rn); }
;                 else { const float k0 = y0 * rn, k1 = y1 * rn; *(unsigned*)(kL + t * GK_STR + 2 * lane) = pk2(k0, k1); const float eg = gL[128 + t], ed = __expf(gl - gL[t]);
;                     kegL[(2 * lane) * GT_STR + t] = f2bf(k0 * eg); kegL[(2 * lane + 1) * GT_STR + t] = f2bf(k1 * eg); kdL[(2 * lane) * GT_STR + t] = f2bf(k0 * ed); kdL[(2 * lane + 1) * GT_STR + t] = f2bf(k1 * ed); } } });
.LBB0_1295:
	s_add_i32 s98, s25, s88
	s_add_i32 s99, s98, 0x1c410
	s_add_i32 s98, s98, 0x1c610
	v_mov_b32_e32 v70, s98
	v_mov_b32_e32 v71, s99
	ds_read_b32 v72, v70
	ds_read_b32 v73, v71
	v_pk_mul_f32 v[44:45], v[2:3], v[20:21]
	s_and_b64 vcc, exec, s[12:13]
	v_pk_fma_f32 v[18:19], v[0:1], v[18:19], v[44:45]
	s_mov_b64 s[16:17], -1
	v_pk_fma_f32 v[18:19], v[4:5], v[22:23], v[18:19]
	v_pk_fma_f32 v[18:19], v[6:7], v[24:25], v[18:19]
	s_nop 0
	v_mul_f32_e32 v26, 0xbfb8aa3b, v18
	v_mul_f32_e32 v31, 0xbfb8aa3b, v19
	v_exp_f32_e32 v26, v26
	v_exp_f32_e32 v31, v31
	v_add_f32_e32 v26, 1.0, v26
	v_add_f32_e32 v31, 1.0, v31
	v_rcp_f32_e32 v44, v26
	v_rcp_f32_e32 v45, v31
	s_nop 0
	v_pk_mul_f32 v[18:19], v[18:19], v[44:45]
	s_cbranch_vccnz .LBB0_1301
	v_pk_mul_f32 v[44:45], v[18:19], v[18:19]
	s_nop 0
	v_add_f32_e32 v26, v44, v45
	s_nop 1
	v_add_f32_dpp v26, v26, v26 quad_perm:[1,0,3,2] row_mask:0xf bank_mask:0xf bound_ctrl:1
	s_nop 1
	v_add_f32_dpp v26, v26, v26 quad_perm:[2,3,0,1] row_mask:0xf bank_mask:0xf bound_ctrl:1
	s_nop 1
	v_add_f32_dpp v26, v26, v26 row_half_mirror row_mask:0xf bank_mask:0xf bound_ctrl:1
	s_nop 1
	v_add_f32_dpp v26, v26, v26 row_mirror row_mask:0xf bank_mask:0xf bound_ctrl:1
	s_nop 0
	v_readlane_b32 s36, v26, 16
	v_readlane_b32 s37, v26, 48
	v_readlane_b32 s16, v26, 0
	v_readlane_b32 s17, v26, 32
	v_mov_b32_e32 v44, s36
	v_mov_b32_e32 v45, s37
	v_pk_add_f32 v[44:45], s[16:17], v[44:45]
	s_mov_b64 s[16:17], -1
	v_add_f32_e32 v26, v44, v45
	v_add_f32_e32 v26, 0x358637bd, v26
	v_mul_f32_e32 v31, 0x4b800000, v26
	v_cmp_gt_f32_e32 vcc, s78, v26
	s_nop 1
	v_cndmask_b32_e32 v26, v26, v31, vcc
	v_rsq_f32_e32 v26, v26
	s_nop 0
	v_mul_f32_e32 v31, 0x45800000, v26
	v_cndmask_b32_e32 v26, v26, v31, vcc
	s_and_b64 vcc, exec, s[8:9]
	s_cbranch_vccnz .LBB0_1298
	s_waitcnt lgkmcnt(2)
	v_pk_mul_f32 v[44:45], v[18:19], v[26:27] op_sel_hi:[1,0]
	v_add_u32_e32 v46, s88, v29
	v_cvt_pk_bf16_f32 v35, v44, v45
	ds_write_b32 v46, v35 offset:18496
	s_waitcnt lgkmcnt(1)
	v_sub_f32_e32 v32, v27, v73
	v_mul_f32_e32 v32, 0x3fb8aa3b, v32
	v_exp_f32_e32 v32, v32
	v_mul_f32_e32 v35, v44, v72
	v_mul_f32_e32 v31, v45, v72
	v_cvt_pk_bf16_f32 v31, v31, s0
	v_cvt_pk_bf16_f32 v35, v35, s0
	ds_write_b16 v30, v31 offset:34968
	v_mul_f32_e32 v31, v44, v32
	ds_write_b16 v30, v35 offset:34824
	v_cvt_pk_bf16_f32 v31, v31, s0
	v_add_u32_e32 v35, 0x11808, v30
	ds_write_b16 v35, v31
	v_mul_f32_e32 v31, v45, v32
	v_cvt_pk_bf16_f32 v31, v31, s0
	v_add_u32_e32 v32, 0x11898, v30
	s_mov_b64 s[16:17], 0
	ds_write_b16 v32, v31

; DI unsigned pk2(float lo, float hi) { f32x2 v = {lo, hi}; bf16x2_t b = __builtin_convertvector(v, bf16x2_t); return __builtin_bit_cast(unsigned, b); }
; DI bf16_t f2bf(float f) { return (bf16_t)(pk2(f, 0.f) & 0xffffu); }
; DI float siluf(float x) { return x * __builtin_amdgcn_rcpf(1.f + __expf(-x)); }
; template <class F> DI void gdn_conv(const Prm& p, int kind, int b, int c, int col, int t0, int n, F f) {
;     ...
;     for (int t = t0; t < t0 + n; ++t) { const f32x2 x3 = gdn_raw(p, kind, b, c, t, col);
;         const float y0 = w[0].x * x0.x + w[1].x * x1.x + w[2].x * x2.x + w[3].x * x3.x, y1 = w[0].y * x0.y + w[1].y * x1.y + w[2].y * x2.y + w[3].y * x3.y;
;         f(t, siluf(y0), siluf(y1)); x0 = x1; x1 = x2; x2 = x3; }
; DI void gdn_pre_unit(const Prm& p, unsigned char* lds0, int u, int tid, int wid, int lane) {
;     ...
;         gdn_conv(p, kind, b, c, part * 512 + h * 128 + 2 * lane, 32 * th, 32, [&](int t, float y0, float y1) {
;             if (part == 2) { vtL[(2 * lane) * GT_STR + t] = f2bf(y0); vtL[(2 * lane + 1) * GT_STR + t] = f2bf(y1); }
;             else { const float ss = wave_sum(y0 * y0 + y1 * y1); float rn = rsqrtf(ss + 1e-6f);
;                 if (part == 0) { rn *= 0.08838834764831845f; *(unsigned*)(qL + t * GK_STR + 2 * lane) = pk2(y0 * rn, y1 * rn); }
;                 else { const float k0 = y0 * rn, k1 = y1 * rn; *(unsigned*)(kL + t * GK_STR + 2 * lane) = pk2(k0, k1); const float eg = gL[128 + t], ed = __expf(gl - gL[t]);
;                     kegL[(2 * lane) * GT_STR + t] = f2bf(k0 * eg); kegL[(2 * lane + 1) * GT_STR + t] = f2bf(k1 * eg); kdL[(2 * lane) * GT_STR + t] = f2bf(k0 * ed); kdL[(2 * lane + 1) * GT_STR + t] = f2bf(k1 * ed); } } });
.LBB0_1313:
	s_add_i32 s98, s25, s88
	s_add_i32 s99, s98, 0x1c414
	s_add_i32 s98, s98, 0x1c614
	v_mov_b32_e32 v70, s98
	v_mov_b32_e32 v71, s99
	ds_read_b32 v72, v70
	ds_read_b32 v73, v71
	v_pk_mul_f32 v[44:45], v[2:3], v[22:23]
	s_and_b64 vcc, exec, s[12:13]
	v_pk_fma_f32 v[20:21], v[0:1], v[20:21], v[44:45]
	s_mov_b64 s[16:17], -1
	v_pk_fma_f32 v[20:21], v[4:5], v[24:25], v[20:21]
	v_pk_fma_f32 v[20:21], v[6:7], v[18:19], v[20:21]
	s_nop 0
	v_mul_f32_e32 v26, 0xbfb8aa3b, v20
	v_mul_f32_e32 v31, 0xbfb8aa3b, v21
	v_exp_f32_e32 v26, v26
	v_exp_f32_e32 v31, v31
	v_add_f32_e32 v26, 1.0, v26
	v_add_f32_e32 v31, 1.0, v31
	v_rcp_f32_e32 v44, v26
	v_rcp_f32_e32 v45, v31
	s_nop 0
	v_pk_mul_f32 v[20:21], v[20:21], v[44:45]
	s_cbranch_vccnz .LBB0_1319
	v_pk_mul_f32 v[44:45], v[20:21], v[20:21]
	s_nop 0
	v_add_f32_e32 v26, v44, v45
	s_nop 1
	v_add_f32_dpp v26, v26, v26 quad_perm:[1,0,3,2] row_mask:0xf bank_mask:0xf bound_ctrl:1
	s_nop 1
	v_add_f32_dpp v26, v26, v26 quad_perm:[2,3,0,1] row_mask:0xf bank_mask:0xf bound_ctrl:1
	s_nop 1
	v_add_f32_dpp v26, v26, v26 row_half_mirror row_mask:0xf bank_mask:0xf bound_ctrl:1
	s_nop 1
	v_add_f32_dpp v26, v26, v26 row_mirror row_mask:0xf bank_mask:0xf bound_ctrl:1
	s_nop 0
	v_readlane_b32 s36, v26, 16
	v_readlane_b32 s37, v26, 48
	v_readlane_b32 s16, v26, 0
	v_readlane_b32 s17, v26, 32
	v_mov_b32_e32 v44, s36
	v_mov_b32_e32 v45, s37
	v_pk_add_f32 v[44:45], s[16:17], v[44:45]
	s_mov_b64 s[16:17], -1
	v_add_f32_e32 v26, v44, v45
	v_add_f32_e32 v26, 0x358637bd, v26
	v_mul_f32_e32 v31, 0x4b800000, v26
	v_cmp_gt_f32_e32 vcc, s78, v26
	s_nop 1
	v_cndmask_b32_e32 v26, v26, v31, vcc
	v_rsq_f32_e32 v26, v26
	s_nop 0
	v_mul_f32_e32 v31, 0x45800000, v26
	v_cndmask_b32_e32 v26, v26, v31, vcc
	s_and_b64 vcc, exec, s[8:9]
	s_cbranch_vccnz .LBB0_1316
	s_waitcnt lgkmcnt(2)
	v_pk_mul_f32 v[44:45], v[20:21], v[26:27] op_sel_hi:[1,0]
	v_add_u32_e32 v46, s88, v29
	v_cvt_pk_bf16_f32 v35, v44, v45
	ds_write_b32 v46, v35 offset:18768
	s_waitcnt lgkmcnt(1)
	v_sub_f32_e32 v32, v27, v73
	v_mul_f32_e32 v32, 0x3fb8aa3b, v32
	v_exp_f32_e32 v32, v32
	v_mul_f32_e32 v35, v44, v72
	v_mul_f32_e32 v31, v45, v72
	v_cvt_pk_bf16_f32 v31, v31, s0
	v_cvt_pk_bf16_f32 v35, v35, s0
	ds_write_b16 v30, v31 offset:34970
	v_mul_f32_e32 v31, v44, v32
	ds_write_b16 v30, v35 offset:34826
	v_cvt_pk_bf16_f32 v31, v31, s0
	v_add_u32_e32 v35, 0x1180a, v30
	ds_write_b16 v35, v31
	v_mul_f32_e32 v31, v45, v32
	v_cvt_pk_bf16_f32 v31, v31, s0
	v_add_u32_e32 v32, 0x1189a, v30
	s_mov_b64 s[16:17], 0
	ds_write_b16 v32, v31

; DI unsigned pk2(float lo, float hi) { f32x2 v = {lo, hi}; bf16x2_t b = __builtin_convertvector(v, bf16x2_t); return __builtin_bit_cast(unsigned, b); }
; DI bf16_t f2bf(float f) { return (bf16_t)(pk2(f, 0.f) & 0xffffu); }
; DI float siluf(float x) { return x * __builtin_amdgcn_rcpf(1.f + __expf(-x)); }
; template <class F> DI void gdn_conv(const Prm& p, int kind, int b, int c, int col, int t0, int n, F f) {
;     ...
;     for (int t = t0; t < t0 + n; ++t) { const f32x2 x3 = gdn_raw(p, kind, b, c, t, col);
;         const float y0 = w[0].x * x0.x + w[1].x * x1.x + w[2].x * x2.x + w[3].x * x3.x, y1 = w[0].y * x0.y + w[1].y * x1.y + w[2].y * x2.y + w[3].y * x3.y;
;         f(t, siluf(y0), siluf(y1)); x0 = x1; x1 = x2; x2 = x3; }
; DI void gdn_pre_unit(const Prm& p, unsigned char* lds0, int u, int tid, int wid, int lane) {
;     ...
;         gdn_conv(p, kind, b, c, part * 512 + h * 128 + 2 * lane, 32 * th, 32, [&](int t, float y0, float y1) {
;             if (part == 2) { vtL[(2 * lane) * GT_STR + t] = f2bf(y0); vtL[(2 * lane + 1) * GT_STR + t] = f2bf(y1); }
;             else { const float ss = wave_sum(y0 * y0 + y1 * y1); float rn = rsqrtf(ss + 1e-6f);
;                 if (part == 0) { rn *= 0.08838834764831845f; *(unsigned*)(qL + t * GK_STR + 2 * lane) = pk2(y0 * rn, y1 * rn); }
;                 else { const float k0 = y0 * rn, k1 = y1 * rn; *(unsigned*)(kL + t * GK_STR + 2 * lane) = pk2(k0, k1); const float eg = gL[128 + t], ed = __expf(gl - gL[t]);
;                     kegL[(2 * lane) * GT_STR + t] = f2bf(k0 * eg); kegL[(2 * lane + 1) * GT_STR + t] = f2bf(k1 * eg); kdL[(2 * lane) * GT_STR + t] = f2bf(k0 * ed); kdL[(2 * lane + 1) * GT_STR + t] = f2bf(k1 * ed); } } });
.LBB0_1331:
	s_add_i32 s98, s25, s88
	s_add_i32 s99, s98, 0x1c418
	s_add_i32 s98, s98, 0x1c618
	v_mov_b32_e32 v70, s98
	v_mov_b32_e32 v71, s99
	ds_read_b32 v72, v70
	ds_read_b32 v73, v71
	v_pk_mul_f32 v[44:45], v[2:3], v[24:25]
	s_and_b64 vcc, exec, s[12:13]
	v_pk_fma_f32 v[22:23], v[0:1], v[22:23], v[44:45]
	s_mov_b64 s[16:17], -1
	v_pk_fma_f32 v[22:23], v[4:5], v[18:19], v[22:23]
	v_pk_fma_f32 v[22:23], v[6:7], v[20:21], v[22:23]
	s_nop 0
	v_mul_f32_e32 v26, 0xbfb8aa3b, v22
	v_mul_f32_e32 v31, 0xbfb8aa3b, v23
	v_exp_f32_e32 v26, v26
	v_exp_f32_e32 v31, v31
	v_add_f32_e32 v26, 1.0, v26
	v_add_f32_e32 v31, 1.0, v31
	v_rcp_f32_e32 v44, v26
	v_rcp_f32_e32 v45, v31
	s_nop 0
	v_pk_mul_f32 v[22:23], v[22:23], v[44:45]
	s_cbranch_vccnz .LBB0_1337
	v_pk_mul_f32 v[44:45], v[22:23], v[22:23]
	s_nop 0
	v_add_f32_e32 v26, v44, v45
	s_nop 1
	v_add_f32_dpp v26, v26, v26 quad_perm:[1,0,3,2] row_mask:0xf bank_mask:0xf bound_ctrl:1
	s_nop 1
	v_add_f32_dpp v26, v26, v26 quad_perm:[2,3,0,1] row_mask:0xf bank_mask:0xf bound_ctrl:1
	s_nop 1
	v_add_f32_dpp v26, v26, v26 row_half_mirror row_mask:0xf bank_mask:0xf bound_ctrl:1
	s_nop 1
	v_add_f32_dpp v26, v26, v26 row_mirror row_mask:0xf bank_mask:0xf bound_ctrl:1
	s_nop 0
	v_readlane_b32 s36, v26, 16
	v_readlane_b32 s37, v26, 48
	v_readlane_b32 s16, v26, 0
	v_readlane_b32 s17, v26, 32
	v_mov_b32_e32 v44, s36
	v_mov_b32_e32 v45, s37
	v_pk_add_f32 v[44:45], s[16:17], v[44:45]
	s_mov_b64 s[16:17], -1
	v_add_f32_e32 v26, v44, v45
	v_add_f32_e32 v26, 0x358637bd, v26
	v_mul_f32_e32 v31, 0x4b800000, v26
	v_cmp_gt_f32_e32 vcc, s78, v26
	s_nop 1
	v_cndmask_b32_e32 v26, v26, v31, vcc
	v_rsq_f32_e32 v26, v26
	s_nop 0
	v_mul_f32_e32 v31, 0x45800000, v26
	v_cndmask_b32_e32 v26, v26, v31, vcc
	s_and_b64 vcc, exec, s[8:9]
	s_cbranch_vccnz .LBB0_1334
	s_waitcnt lgkmcnt(2)
	v_pk_mul_f32 v[44:45], v[22:23], v[26:27] op_sel_hi:[1,0]
	v_add_u32_e32 v46, s88, v29
	v_cvt_pk_bf16_f32 v35, v44, v45
	ds_write_b32 v46, v35 offset:19040
	s_waitcnt lgkmcnt(1)
	v_sub_f32_e32 v32, v27, v73
	v_mul_f32_e32 v32, 0x3fb8aa3b, v32
	v_exp_f32_e32 v32, v32
	v_mul_f32_e32 v35, v44, v72
	v_mul_f32_e32 v31, v45, v72
	v_cvt_pk_bf16_f32 v31, v31, s0
	v_cvt_pk_bf16_f32 v35, v35, s0
	ds_write_b16 v30, v31 offset:34972
	v_mul_f32_e32 v31, v44, v32
	ds_write_b16 v30, v35 offset:34828
	v_cvt_pk_bf16_f32 v31, v31, s0
	v_add_u32_e32 v35, 0x1180c, v30
	ds_write_b16 v35, v31
	v_mul_f32_e32 v31, v45, v32
	v_cvt_pk_bf16_f32 v31, v31, s0
	v_add_u32_e32 v32, 0x1189c, v30
	s_mov_b64 s[16:17], 0
	ds_write_b16 v32, v31

; DI unsigned pk2(float lo, float hi) { f32x2 v = {lo, hi}; bf16x2_t b = __builtin_convertvector(v, bf16x2_t); return __builtin_bit_cast(unsigned, b); }
; DI bf16_t f2bf(float f) { return (bf16_t)(pk2(f, 0.f) & 0xffffu); }
; DI float siluf(float x) { return x * __builtin_amdgcn_rcpf(1.f + __expf(-x)); }
; template <class F> DI void gdn_conv(const Prm& p, int kind, int b, int c, int col, int t0, int n, F f) {
;     ...
;     for (int t = t0; t < t0 + n; ++t) { const f32x2 x3 = gdn_raw(p, kind, b, c, t, col);
;         const float y0 = w[0].x * x0.x + w[1].x * x1.x + w[2].x * x2.x + w[3].x * x3.x, y1 = w[0].y * x0.y + w[1].y * x1.y + w[2].y * x2.y + w[3].y * x3.y;
;         f(t, siluf(y0), siluf(y1)); x0 = x1; x1 = x2; x2 = x3; }
; DI void gdn_pre_unit(const Prm& p, unsigned char* lds0, int u, int tid, int wid, int lane) {
;     ...
;         gdn_conv(p, kind, b, c, part * 512 + h * 128 + 2 * lane, 32 * th, 32, [&](int t, float y0, float y1) {
;             if (part == 2) { vtL[(2 * lane) * GT_STR + t] = f2bf(y0); vtL[(2 * lane + 1) * GT_STR + t] = f2bf(y1); }
;             else { const float ss = wave_sum(y0 * y0 + y1 * y1); float rn = rsqrtf(ss + 1e-6f);
;                 if (part == 0) { rn *= 0.08838834764831845f; *(unsigned*)(qL + t * GK_STR + 2 * lane) = pk2(y0 * rn, y1 * rn); }
;                 else { const float k0 = y0 * rn, k1 = y1 * rn; *(unsigned*)(kL + t * GK_STR + 2 * lane) = pk2(k0, k1); const float eg = gL[128 + t], ed = __expf(gl - gL[t]);
;                     kegL[(2 * lane) * GT_STR + t] = f2bf(k0 * eg); kegL[(2 * lane + 1) * GT_STR + t] = f2bf(k1 * eg); kdL[(2 * lane) * GT_STR + t] = f2bf(k0 * ed); kdL[(2 * lane + 1) * GT_STR + t] = f2bf(k1 * ed); } } });
.LBB0_1349:
	s_add_i32 s98, s25, s88
	s_add_i32 s99, s98, 0x1c61c
	s_add_i32 s98, s98, 0x1c41c
	v_mov_b32_e32 v70, s98
	v_mov_b32_e32 v71, s99
	ds_read_b32 v72, v70
	ds_read_b32 v73, v71
	v_pk_mul_f32 v[44:45], v[2:3], v[18:19]
	s_and_b64 vcc, exec, s[12:13]
	v_pk_fma_f32 v[24:25], v[0:1], v[24:25], v[44:45]
	s_mov_b64 s[6:7], -1
	v_pk_fma_f32 v[24:25], v[4:5], v[20:21], v[24:25]
	v_pk_fma_f32 v[24:25], v[6:7], v[22:23], v[24:25]
	s_nop 0
	v_mul_f32_e32 v26, 0xbfb8aa3b, v24
	v_mul_f32_e32 v31, 0xbfb8aa3b, v25
	v_exp_f32_e32 v26, v26
	v_exp_f32_e32 v31, v31
	v_add_f32_e32 v26, 1.0, v26
	v_add_f32_e32 v31, 1.0, v31
	v_rcp_f32_e32 v44, v26
	v_rcp_f32_e32 v45, v31
	s_nop 0
	v_pk_mul_f32 v[24:25], v[24:25], v[44:45]
	s_cbranch_vccnz .LBB0_1355
	v_pk_mul_f32 v[44:45], v[24:25], v[24:25]
	s_nop 0
	v_add_f32_e32 v26, v44, v45
	s_nop 1
	v_add_f32_dpp v26, v26, v26 quad_perm:[1,0,3,2] row_mask:0xf bank_mask:0xf bound_ctrl:1
	s_nop 1
	v_add_f32_dpp v26, v26, v26 quad_perm:[2,3,0,1] row_mask:0xf bank_mask:0xf bound_ctrl:1
	s_nop 1
	v_add_f32_dpp v26, v26, v26 row_half_mirror row_mask:0xf bank_mask:0xf bound_ctrl:1
	s_nop 1
	v_add_f32_dpp v26, v26, v26 row_mirror row_mask:0xf bank_mask:0xf bound_ctrl:1
	s_nop 0
	v_readlane_b32 s10, v26, 16
	v_readlane_b32 s11, v26, 48
	v_readlane_b32 s6, v26, 0
	v_readlane_b32 s7, v26, 32
	v_mov_b32_e32 v44, s10
	v_mov_b32_e32 v45, s11
	v_pk_add_f32 v[44:45], s[6:7], v[44:45]
	s_mov_b64 s[6:7], -1
	v_add_f32_e32 v26, v44, v45
	v_add_f32_e32 v26, 0x358637bd, v26
	v_mul_f32_e32 v31, 0x4b800000, v26
	v_cmp_gt_f32_e32 vcc, s78, v26
	s_nop 1
	v_cndmask_b32_e32 v26, v26, v31, vcc
	v_rsq_f32_e32 v26, v26
	s_nop 0
	v_mul_f32_e32 v31, 0x45800000, v26
	v_cndmask_b32_e32 v26, v26, v31, vcc
	s_and_b64 vcc, exec, s[8:9]
	v_add_u32_e32 v31, s88, v29
	s_cbranch_vccnz .LBB0_1352
	s_waitcnt lgkmcnt(2)
	v_pk_mul_f32 v[44:45], v[24:25], v[26:27] op_sel_hi:[1,0]
	s_mov_b64 s[6:7], 0
	v_cvt_pk_bf16_f32 v46, v44, v45
	s_waitcnt lgkmcnt(1)
	v_sub_f32_e32 v35, v27, v72
	v_mul_f32_e32 v35, 0x3fb8aa3b, v35
	v_exp_f32_e32 v35, v35
	ds_write_b32 v31, v46 offset:19312
	s_waitcnt lgkmcnt(1)
	v_mul_f32_e32 v46, v44, v73
	v_mul_f32_e32 v32, v45, v73
	v_cvt_pk_bf16_f32 v32, v32, s0
	ds_write_b16 v30, v32 offset:34974
	v_mul_f32_e32 v32, v44, v35
	v_cvt_pk_bf16_f32 v32, v32, s0
	v_add_u32_e32 v44, 0x1180e, v30
	ds_write_b16 v44, v32
	v_mul_f32_e32 v32, v45, v35
	v_cvt_pk_bf16_f32 v46, v46, s0
	v_cvt_pk_bf16_f32 v32, v32, s0
	v_add_u32_e32 v35, 0x1189e, v30
	ds_write_b16 v30, v46 offset:34830
	ds_write_b16 v35, v32
